# barrier: on global seams non-leaders poll the cross-XCD release generation directly (own count of global barriers, exact-match wait); XCD word still used on XCD-local seams
# speedup vs baseline: 1.0134x; 1.0134x over previous
; #define LAS __attribute__((address_space(3)))
; __global__ void __launch_bounds__(NTHR, 2) hybrid_fwd(Args args) {
;     extern __shared__ __attribute__((aligned(16))) unsigned char lds_raw[];
;     LAS unsigned char* lds = (LAS unsigned char*)lds_raw;
;     cg::grid_group grid = cg::this_grid();
;     volatile LAS unsigned* MISC = (volatile LAS unsigned*)(lds + LDS_BYTES - 64);
;     volatile LAS unsigned* PT = (volatile LAS unsigned*)(lds + LDS_BYTES - 256);
;     if (threadIdx.x < 16) MISC[threadIdx.x] = 0u;
;     if (threadIdx.x == 0) {
;     ...
;         PUTP(0) PUTP(1) PUTP(2) PUTP(3) PUTP(4) PUTP(5) PUTP(6) PUTP(7) PUTP(8) PUTP(9) PUTP(10) PUTP(11) PUTP(12) PUTP(13)
;     ...
;     }
_Z10hybrid_fwd4Args:
	s_mov_b32 s27, s2
	s_mov_b32 s101, 0
	v_writelane_b32 v255, s101, 21
	s_load_dword s2, s[0:1], 0x88
	s_load_dwordx2 s[96:97], s[0:1], 0x80
	s_add_u32 s4, s0, 0x80
	s_addc_u32 s5, s1, 0
	v_and_b32_e32 v218, 0x3ff, v0
	v_writelane_b32 v252, s4, 0
	v_cmp_gt_u32_e32 vcc, 16, v218
	s_nop 0
	v_writelane_b32 v252, s5, 1
	s_and_saveexec_b64 s[4:5], vcc
	v_lshl_add_u32 v1, v218, 2, 0
	v_add_u32_e32 v1, 0x23fc0, v1
	v_mov_b32_e32 v2, 0
	ds_write_b32 v1, v2
	s_or_b64 exec, exec, s[4:5]
	s_load_dwordx16 s[36:51], s[0:1], 0x40
	v_cmp_eq_u32_e64 s[86:87], 0, v218
	s_and_saveexec_b64 s[20:21], s[86:87]
	s_cbranch_execz .LBB0_4
	s_load_dwordx16 s[4:19], s[0:1], 0x0
	s_add_i32 s0, 0, 0x23f00
	s_add_i32 s1, 0, 0x23f04
	v_mov_b32_e32 v1, s0
	v_mov_b32_e32 v2, s1
	s_waitcnt lgkmcnt(0)
	v_mov_b32_e32 v3, s4
	ds_write_b32 v1, v3
	v_mov_b32_e32 v1, s5
	s_add_i32 s0, 0, 0x23f08
	ds_write_b32 v2, v1
	v_mov_b32_e32 v1, s0
	v_mov_b32_e32 v2, s6
	s_add_i32 s0, 0, 0x23f0c
	ds_write_b32 v1, v2
	v_mov_b32_e32 v1, s0
	v_mov_b32_e32 v2, s7
	s_add_i32 s0, 0, 0x23f10
	ds_write_b32 v1, v2
	v_mov_b32_e32 v1, s0
	v_mov_b32_e32 v2, s8
	s_add_i32 s0, 0, 0x23f14
	ds_write_b32 v1, v2
	v_mov_b32_e32 v1, s0
	v_mov_b32_e32 v2, s9
	s_add_i32 s0, 0, 0x23f18
	ds_write_b32 v1, v2
	v_mov_b32_e32 v1, s0
	v_mov_b32_e32 v2, s10
	s_add_i32 s0, 0, 0x23f1c
	ds_write_b32 v1, v2
	v_mov_b32_e32 v1, s0
	v_mov_b32_e32 v2, s11
	s_add_i32 s0, 0, 0x23f20
	ds_write_b32 v1, v2
	v_mov_b32_e32 v1, s0
	v_mov_b32_e32 v2, s12
	s_add_i32 s0, 0, 0x23f24
	ds_write_b32 v1, v2
	v_mov_b32_e32 v1, s0
	v_mov_b32_e32 v2, s13
	s_add_i32 s0, 0, 0x23f28
	ds_write_b32 v1, v2
	v_mov_b32_e32 v1, s0
	v_mov_b32_e32 v2, s14
	s_add_i32 s0, 0, 0x23f2c
	ds_write_b32 v1, v2
	v_mov_b32_e32 v1, s0
	v_mov_b32_e32 v2, s15
	s_add_i32 s0, 0, 0x23f30
	ds_write_b32 v1, v2
	v_mov_b32_e32 v1, s0
	v_mov_b32_e32 v2, s16
	s_add_i32 s0, 0, 0x23f34
	ds_write_b32 v1, v2
	v_mov_b32_e32 v1, s0
	v_mov_b32_e32 v2, s17
	s_add_i32 s0, 0, 0x23f38
	ds_write_b32 v1, v2
	v_mov_b32_e32 v1, s0
	v_mov_b32_e32 v2, s18
	s_add_i32 s0, 0, 0x23f3c
	ds_write_b32 v1, v2
	v_mov_b32_e32 v1, s0
	v_mov_b32_e32 v2, s19
	s_add_i32 s0, 0, 0x23f40
	ds_write_b32 v1, v2
	v_mov_b32_e32 v1, s0
	v_mov_b32_e32 v2, s36
	s_add_i32 s0, 0, 0x23f44
	ds_write_b32 v1, v2
	v_mov_b32_e32 v1, s0
	v_mov_b32_e32 v2, s37
	s_add_i32 s0, 0, 0x23f48
	ds_write_b32 v1, v2
	v_mov_b32_e32 v1, s0
	v_mov_b32_e32 v2, s38
	s_add_i32 s0, 0, 0x23f4c
	ds_write_b32 v1, v2
	v_mov_b32_e32 v1, s0
	v_mov_b32_e32 v2, s39
	s_add_i32 s0, 0, 0x23f50
	ds_write_b32 v1, v2
	v_mov_b32_e32 v1, s0
	v_mov_b32_e32 v2, s40
	s_add_i32 s0, 0, 0x23f54
	ds_write_b32 v1, v2
	v_mov_b32_e32 v1, s0
	v_mov_b32_e32 v2, s41
	s_add_i32 s0, 0, 0x23f58
	ds_write_b32 v1, v2
	v_mov_b32_e32 v1, s0
	v_mov_b32_e32 v2, s42
	s_add_i32 s0, 0, 0x23f5c
	ds_write_b32 v1, v2
	v_mov_b32_e32 v1, s0
	v_mov_b32_e32 v2, s43
	s_add_i32 s0, 0, 0x23f60
	ds_write_b32 v1, v2
	v_mov_b32_e32 v1, s0
	v_mov_b32_e32 v2, s44
	s_add_i32 s0, 0, 0x23f64
	ds_write_b32 v1, v2
	v_mov_b32_e32 v1, s0
	v_mov_b32_e32 v2, s45
	s_add_i32 s0, 0, 0x23f68
	ds_write_b32 v1, v2
	v_mov_b32_e32 v1, s0
	v_mov_b32_e32 v2, s46
	s_add_i32 s0, 0, 0x23f6c
	ds_write_b32 v1, v2
	v_mov_b32_e32 v1, s0
	v_mov_b32_e32 v2, s47
	ds_write_b32 v1, v2

; __device__ __forceinline__ void xcd_barrier(const XcdBarrier& b) {
;     asm volatile("s_waitcnt vmcnt(0)" ::: "memory");
;     __syncthreads();
;     if (threadIdx.x == 0) {
;         unsigned* bar = b.bar;
;         __builtin_amdgcn_s_waitcnt(0);
;         unsigned nloc = b.st[0], nx = b.st[1];
;         if (nloc == 0u) { xcd_barrier_complete(bar, b.x, nloc, nx); b.st[0] = nloc; b.st[1] = nx; }
.Lxl_flag_done:
	s_cmp_eq_u32 s101, 0
	s_cbranch_scc1 .Ltg_global
	s_cmp_lt_i32 s97, 1
	s_cbranch_scc1 .Ltg_global
	s_mul_i32 s2, s97, 0xcd
	s_lshr_b32 s2, s2, 10
	s_mul_i32 s2, s2, 5
	s_sub_i32 s2, s97, s2
	s_cmp_eq_u32 s2, 1
	s_cbranch_scc1 .Ltg_local
	s_cmp_eq_u32 s2, 4
	s_cbranch_scc1 .Ltg_local
.Ltg_global:
	v_readlane_b32 s100, v255, 21
	s_nop 3
	s_add_i32 s2, s100, 1
	v_writelane_b32 v255, s2, 21
	s_branch .Ltg_done
.Ltg_local:
	s_mov_b32 s100, -1
.Ltg_done:
	v_readlane_b32 s2, v254, 28
	s_waitcnt vmcnt(0) expcnt(0) lgkmcnt(0)
	s_nop 0
	v_mov_b32_e32 v0, s2
	ds_read_b32 v2, v0
	v_readlane_b32 s2, v254, 29
	s_waitcnt lgkmcnt(0)
	v_cmp_ne_u32_e32 vcc, 0, v2
	v_mov_b32_e32 v0, s2
	ds_read_b32 v0, v0
	s_cbranch_vccnz .LBB0_378
	s_mov_b32 s2, 1
	s_branch .LBB0_366

; __device__ __forceinline__ unsigned xb_ld(unsigned* p)              { return __hip_atomic_load(p, __ATOMIC_RELAXED, __HIP_MEMORY_SCOPE_AGENT); }
; __device__ __forceinline__ unsigned xb_add(unsigned* p, unsigned v) { return __hip_atomic_fetch_add(p, v, __ATOMIC_RELAXED, __HIP_MEMORY_SCOPE_AGENT); }
; #define XB_SPIN(cond, bar) do { unsigned _sp = 0; while (cond) { __builtin_amdgcn_s_sleep(1); \
;     if ((++_sp & 255u) == 0u) { if (xb_ld(&(bar)[XB_TMO])) break; if (_sp > XB_SPIN_CAP) { atomicAdd(&(bar)[XB_TMO], 1u); break; } } } } while (0)
; __device__ __forceinline__ void xcd_barrier(const XcdBarrier& b) {
;     ...
;         const unsigned gen = old / nloc;
;         if (old + 1u == (gen + 1u) * nloc) {
;             __builtin_amdgcn_fence(__ATOMIC_RELEASE, "agent");
;             asm volatile("s_waitcnt vmcnt(0)" ::: "memory");
;             const unsigned og = xb_add(&bar[XB_TOP], 1u);
;             const unsigned tg = og / nx;
;             if (og + 1u == (tg + 1u) * nx) xb_add(&bar[XB_TOPGEN], 1u);
;             else XB_SPIN(xb_ld(&bar[XB_TOPGEN]) == tg, bar);
;             __builtin_amdgcn_fence(__ATOMIC_ACQUIRE, "agent");
;             xb_add(&bar[XB_XGEN(b.x)], 1u);
;             asm volatile("s_waitcnt vmcnt(0)" ::: "memory");
;         } else {
;             XB_SPIN(xb_ld(&bar[XB_XGEN(b.x)]) == gen, bar);
.LBB0_380:
	s_or_b64 exec, exec, s[6:7]
	buffer_inv sc1
	v_cvt_f32_u32_e32 v4, v2
	s_waitcnt vmcnt(1)
	v_readfirstlane_b32 s2, v3
	v_sub_u32_e32 v3, 0, v2
	v_rcp_iflag_f32_e32 v4, v4
	v_add_u32_e32 v5, s2, v1
	v_mul_f32_e32 v4, 0x4f7ffffe, v4
	v_cvt_u32_f32_e32 v4, v4
	v_mul_lo_u32 v1, v3, v4
	v_mul_hi_u32 v1, v4, v1
	v_add_u32_e32 v1, v4, v1
	v_mul_hi_u32 v1, v5, v1
	v_mul_lo_u32 v3, v1, v2
	v_sub_u32_e32 v3, v5, v3
	v_add_u32_e32 v4, 1, v1
	v_cmp_ge_u32_e32 vcc, v3, v2
	s_nop 1
	v_cndmask_b32_e32 v1, v1, v4, vcc
	v_sub_u32_e32 v4, v3, v2
	v_cndmask_b32_e32 v3, v3, v4, vcc
	v_add_u32_e32 v4, 1, v1
	v_cmp_ge_u32_e32 vcc, v3, v2
	v_add_u32_e32 v3, 1, v5
	s_nop 0
	v_cndmask_b32_e32 v1, v1, v4, vcc
	v_mul_lo_u32 v4, v2, v1
	v_add_u32_e32 v2, v4, v2
	v_cmp_ne_u32_e32 vcc, v3, v2
	s_and_saveexec_b64 s[6:7], vcc
	s_xor_b64 s[6:7], exec, s[6:7]
	s_cbranch_execz .LBB0_394
	s_cmp_lt_i32 s100, 0
	s_cbranch_scc1 .Ltg_poll_local
	v_readlane_b32 s20, v253, 42
	v_readlane_b32 s21, v253, 43
	v_mov_b32_e32 v1, s100
	s_branch .Ltg_poll_go
.Ltg_poll_local:
	v_readlane_b32 s20, v253, 22
	v_readlane_b32 s21, v253, 23
.Ltg_poll_go:
	v_add_u32_e32 v1, 1, v1
	s_waitcnt lgkmcnt(0)
	s_nop 3
	global_load_dword v0, v193, s[20:21] sc1
	s_waitcnt vmcnt(0)
	v_cmp_ne_u32_e32 vcc, v0, v1
	s_and_saveexec_b64 s[8:9], vcc
	s_cbranch_execz .LBB0_393
	s_mov_b32 s2, 1
	s_mov_b64 s[10:11], 0
	s_branch .LBB0_384

; __device__ __forceinline__ unsigned xb_ld(unsigned* p)              { return __hip_atomic_load(p, __ATOMIC_RELAXED, __HIP_MEMORY_SCOPE_AGENT); }
; #define XB_SPIN(cond, bar) do { unsigned _sp = 0; while (cond) { __builtin_amdgcn_s_sleep(1); \
;     if ((++_sp & 255u) == 0u) { if (xb_ld(&(bar)[XB_TMO])) break; if (_sp > XB_SPIN_CAP) { atomicAdd(&(bar)[XB_TMO], 1u); break; } } } } while (0)
; __device__ __forceinline__ void xcd_barrier(const XcdBarrier& b) {
;     ...
;             XB_SPIN(xb_ld(&bar[XB_XGEN(b.x)]) == gen, bar);
.LBB0_388:
	s_mov_b64 s[14:15], s[20:21]
	s_add_i32 s2, s2, 1
	s_mov_b64 s[16:17], -1
	s_nop 2
	global_load_dword v0, v193, s[14:15] sc1
	s_waitcnt vmcnt(0)
	v_cmp_eq_u32_e32 vcc, v0, v1
	s_orn2_b64 s[14:15], vcc, exec
	s_branch .LBB0_383
